# grid barriers 2-5: the half-way arriver of each XCD issues an early L2 writeback (fire and forget) so the last arriver's flush is shorter
# baseline (speedup 1.0000x reference)
; __device__ __forceinline__ unsigned xb_add(unsigned* p, unsigned v) { return __hip_atomic_fetch_add(p, v, __ATOMIC_RELAXED, __HIP_MEMORY_SCOPE_AGENT); }
; __device__ __forceinline__ XbState xcd_barrier_arrive(const XcdBarrier& b) {
;     asm volatile("s_waitcnt vmcnt(0)" ::: "memory");
;     __syncthreads();
;     unsigned* bar = b.bar;
;     XbState st; st.gen = 0u; st.tg = 0u; st.lastx = false; st.lastt = false;
;     if (threadIdx.x == 0) {
;         __builtin_amdgcn_s_waitcnt(0);
;         unsigned nloc = b.st[0], nx = b.st[1];
;         if (nloc == 0u) { xcd_barrier_complete(bar, b.x, nloc, nx); b.st[0] = nloc; b.st[1] = nx; }
;         const unsigned old = xb_add(&bar[XB_XSUB(b.x)], 1u);
;         st.gen = old / nloc; st.lastx = (old + 1u == (st.gen + 1u) * nloc);
;         if (st.lastx) {
;             __builtin_amdgcn_fence(__ATOMIC_RELEASE, "agent");
;             asm volatile("s_waitcnt vmcnt(0)" ::: "memory");
;             const unsigned og = xb_add(&bar[XB_TOP], 1u);
;             st.tg = og / nx; st.lastt = (og + 1u == (st.tg + 1u) * nx);
;             if (st.lastt) xb_add(&bar[XB_TOPGEN], 1u);
;         }
.Lside_done:
	s_waitcnt vmcnt(0)
	v_mov_b32_e32 v3, 0
	s_mov_b64 s[8:9], 0
	s_waitcnt lgkmcnt(0)
	s_mov_b64 s[6:7], 0
	v_mov_b32_e32 v2, 0
	s_waitcnt vmcnt(0)
	s_barrier
	s_and_saveexec_b64 s[4:5], s[14:15]
	s_cbranch_execz .LBB0_382
	s_waitcnt vmcnt(0) lgkmcnt(0)
	v_mov_b32_e32 v1, 0x27c20
	ds_read_b32 v3, v1
	ds_read_b32 v4, v1 offset:4
	buffer_inv sc1
	s_lshl_b32 s8, s33, 8
	s_add_u32 s8, s82, s8
	s_addc_u32 s9, s83, 0
	v_mov_b32_e32 v1, 0x1000
	v_mov_b32_e32 v5, 1
	global_atomic_add v6, v1, v5, s[8:9] offset:1024 sc0
	s_waitcnt vmcnt(0) lgkmcnt(0)
	v_add_u32_e32 v6, 1, v6
	v_mul_u32_u24_e32 v7, 2, v3
	v_mul_u32_u24_e32 v2, 2, v4
	v_lshrrev_b32_e32 v1, 1, v3
	v_sub_u32_e32 v1, v7, v1
	v_cmp_eq_u32_e32 vcc, v6, v1
	s_and_saveexec_b64 s[8:9], vcc
	s_cbranch_execz .Lbar2_noearly
	buffer_wbl2 sc1
.Lbar2_noearly:
	s_or_b64 exec, exec, s[8:9]
	v_cmp_eq_u32_e32 vcc, v6, v7
	s_and_saveexec_b64 s[8:9], vcc
	s_cbranch_execz .Lbar2_notlast
	buffer_wbl2 sc1
	s_waitcnt vmcnt(0)
	v_mov_b32_e32 v1, 0x7000
	global_atomic_add v1, v5, s[30:31] offset:1024

; __device__ __forceinline__ unsigned xb_add(unsigned* p, unsigned v) { return __hip_atomic_fetch_add(p, v, __ATOMIC_RELAXED, __HIP_MEMORY_SCOPE_AGENT); }
; __device__ __forceinline__ XbState xcd_barrier_arrive(const XcdBarrier& b) {
;     ...
;     if (threadIdx.x == 0) {
;         __builtin_amdgcn_s_waitcnt(0);
;         unsigned nloc = b.st[0], nx = b.st[1];
;         if (nloc == 0u) { xcd_barrier_complete(bar, b.x, nloc, nx); b.st[0] = nloc; b.st[1] = nx; }
;         const unsigned old = xb_add(&bar[XB_XSUB(b.x)], 1u);
;         st.gen = old / nloc; st.lastx = (old + 1u == (st.gen + 1u) * nloc);
;         if (st.lastx) {
;             __builtin_amdgcn_fence(__ATOMIC_RELEASE, "agent");
;             asm volatile("s_waitcnt vmcnt(0)" ::: "memory");
;             const unsigned og = xb_add(&bar[XB_TOP], 1u);
;             st.tg = og / nx; st.lastt = (og + 1u == (st.tg + 1u) * nx);
;             if (st.lastt) xb_add(&bar[XB_TOPGEN], 1u);
.LBB0_565:
	s_waitcnt vmcnt(0)
	v_mov_b32_e32 v3, 0
	s_waitcnt lgkmcnt(0)
	s_mov_b64 s[16:17], 0
	s_mov_b64 s[8:9], 0
	v_mov_b32_e32 v2, 0
	s_barrier
	s_and_saveexec_b64 s[6:7], s[14:15]
	s_cbranch_execz .LBB0_592
	s_waitcnt vmcnt(0) lgkmcnt(0)
	v_mov_b32_e32 v1, 0x27c20
	ds_read_b32 v3, v1
	ds_read_b32 v4, v1 offset:4
	buffer_inv sc1
	s_lshl_b32 s8, s33, 8
	s_add_u32 s8, s82, s8
	s_addc_u32 s9, s83, 0
	v_mov_b32_e32 v1, 0x1000
	v_mov_b32_e32 v5, 1
	global_atomic_add v6, v1, v5, s[8:9] offset:1024 sc0
	s_waitcnt vmcnt(0) lgkmcnt(0)
	v_add_u32_e32 v6, 1, v6
	v_mul_u32_u24_e32 v7, 3, v3
	v_mul_u32_u24_e32 v2, 3, v4
	v_lshrrev_b32_e32 v1, 1, v3
	v_sub_u32_e32 v1, v7, v1
	v_cmp_eq_u32_e32 vcc, v6, v1
	s_and_saveexec_b64 s[8:9], vcc
	s_cbranch_execz .Lbar3_noearly
	buffer_wbl2 sc1

; __device__ __forceinline__ unsigned xb_add(unsigned* p, unsigned v) { return __hip_atomic_fetch_add(p, v, __ATOMIC_RELAXED, __HIP_MEMORY_SCOPE_AGENT); }
; __device__ __forceinline__ XbState xcd_barrier_arrive(const XcdBarrier& b) {
;     ...
;     if (threadIdx.x == 0) {
;         __builtin_amdgcn_s_waitcnt(0);
;         unsigned nloc = b.st[0], nx = b.st[1];
;         if (nloc == 0u) { xcd_barrier_complete(bar, b.x, nloc, nx); b.st[0] = nloc; b.st[1] = nx; }
;         const unsigned old = xb_add(&bar[XB_XSUB(b.x)], 1u);
;         st.gen = old / nloc; st.lastx = (old + 1u == (st.gen + 1u) * nloc);
;         if (st.lastx) {
;             __builtin_amdgcn_fence(__ATOMIC_RELEASE, "agent");
;             asm volatile("s_waitcnt vmcnt(0)" ::: "memory");
;             const unsigned og = xb_add(&bar[XB_TOP], 1u);
;             st.tg = og / nx; st.lastt = (og + 1u == (st.tg + 1u) * nx);
;             if (st.lastt) xb_add(&bar[XB_TOPGEN], 1u);
.LBB0_670:
	s_waitcnt vmcnt(0)
	v_mov_b32_e32 v3, 0
	s_mov_b64 s[16:17], 0
	s_mov_b64 s[8:9], 0
	v_mov_b32_e32 v2, 0
	s_barrier
	s_and_saveexec_b64 s[6:7], s[14:15]
	s_cbranch_execz .LBB0_697
	s_waitcnt vmcnt(0) lgkmcnt(0)
	v_mov_b32_e32 v1, 0x27c20
	ds_read_b32 v3, v1
	ds_read_b32 v4, v1 offset:4
	buffer_inv sc1
	s_lshl_b32 s8, s33, 8
	s_add_u32 s8, s82, s8
	s_addc_u32 s9, s83, 0
	v_mov_b32_e32 v1, 0x1000
	v_mov_b32_e32 v5, 1
	global_atomic_add v6, v1, v5, s[8:9] offset:1024 sc0
	s_waitcnt vmcnt(0) lgkmcnt(0)
	v_add_u32_e32 v6, 1, v6
	v_mul_u32_u24_e32 v7, 4, v3
	v_mul_u32_u24_e32 v2, 4, v4
	v_lshrrev_b32_e32 v1, 1, v3
	v_sub_u32_e32 v1, v7, v1
	v_cmp_eq_u32_e32 vcc, v6, v1
	s_and_saveexec_b64 s[8:9], vcc
	s_cbranch_execz .Lbar4_noearly
	buffer_wbl2 sc1

; __device__ __forceinline__ unsigned xb_add(unsigned* p, unsigned v) { return __hip_atomic_fetch_add(p, v, __ATOMIC_RELAXED, __HIP_MEMORY_SCOPE_AGENT); }
; __device__ __forceinline__ XbState xcd_barrier_arrive(const XcdBarrier& b) {
;     ...
;     if (threadIdx.x == 0) {
;         __builtin_amdgcn_s_waitcnt(0);
;         unsigned nloc = b.st[0], nx = b.st[1];
;         if (nloc == 0u) { xcd_barrier_complete(bar, b.x, nloc, nx); b.st[0] = nloc; b.st[1] = nx; }
;         const unsigned old = xb_add(&bar[XB_XSUB(b.x)], 1u);
;         st.gen = old / nloc; st.lastx = (old + 1u == (st.gen + 1u) * nloc);
;         if (st.lastx) {
;             __builtin_amdgcn_fence(__ATOMIC_RELEASE, "agent");
;             asm volatile("s_waitcnt vmcnt(0)" ::: "memory");
;             const unsigned og = xb_add(&bar[XB_TOP], 1u);
;             st.tg = og / nx; st.lastt = (og + 1u == (st.tg + 1u) * nx);
;             if (st.lastt) xb_add(&bar[XB_TOPGEN], 1u);
;         }
.LBB0_772:
	s_waitcnt vmcnt(0)
	v_mov_b32_e32 v67, 0
	s_mov_b64 s[10:11], 0
	s_mov_b64 s[8:9], 0
	v_mov_b32_e32 v66, 0
	s_waitcnt vmcnt(0)
	s_barrier
	s_and_saveexec_b64 s[6:7], s[14:15]
	s_cbranch_execz .LBB0_799
	s_waitcnt vmcnt(0) lgkmcnt(0)
	v_mov_b32_e32 v3, 0x27c20
	ds_read_b32 v1, v3
	ds_read_b32 v2, v3 offset:4
	buffer_inv sc1
	s_lshl_b32 s8, s33, 8
	s_add_u32 s8, s82, s8
	s_addc_u32 s9, s83, 0
	v_mov_b32_e32 v3, 0x1000
	v_mov_b32_e32 v4, 1
	global_atomic_add v5, v3, v4, s[8:9] offset:1024 sc0
	s_waitcnt vmcnt(0) lgkmcnt(0)
	v_add_u32_e32 v5, 1, v5
	v_mul_u32_u24_e32 v6, 5, v1
	v_mul_u32_u24_e32 v66, 5, v2
	v_lshrrev_b32_e32 v3, 1, v1
	v_sub_u32_e32 v3, v6, v3
	v_cmp_eq_u32_e32 vcc, v5, v3
	s_and_saveexec_b64 s[8:9], vcc
	s_cbranch_execz .Lbar5_noearly
	buffer_wbl2 sc1
.Lbar5_noearly:
	s_or_b64 exec, exec, s[8:9]
	v_cmp_eq_u32_e32 vcc, v5, v6
	s_and_saveexec_b64 s[8:9], vcc
	s_cbranch_execz .Lbar5_notlast
	buffer_wbl2 sc1
	s_waitcnt vmcnt(0)
	v_mov_b32_e32 v3, 0x7000
	global_atomic_add v3, v4, s[30:31] offset:1024
